# MLP1 GEMM: bias loads hoisted ahead of the K-loop into spare VGPRs; epilogue wait relaxed to vmcnt(6) so the next tile's LDS-DMA prefetch stays in flight
# speedup vs baseline: 1.0033x; 1.0033x over previous
; __device__ __forceinline__ unsigned pk2(float lo, float hi) { const v2f_t f = {lo, hi}; const v2bf_t b = __builtin_convertvector(f, v2bf_t); return __builtin_bit_cast(unsigned, b); }
; template <class Epi>
; __device__ __forceinline__ void gemm_phase(LAS unsigned char* lds, const Gemm g, StaticOrder S, const Epi& E) {
;     ...
; #pragma unroll
;         for (int a = 0; a < 2; ++a)
; #pragma unroll
;             for (int b = 0; b < 2; ++b)
; #pragma unroll
;                 for (int m = 0; m < 4; ++m)
; #pragma unroll
;                     for (int n = 0; n < 2; ++n) acc[a][b][m][n] = (f32x4){0.f, 0.f, 0.f, 0.f};
;     __device__ __forceinline__ void operator()(const f32x4 (&acc)[2][2][4][2], const Unit& u, int wr, int wc, int fr, int fq) const {
;     ...
;         f32x4 bv[2][2];
; #pragma unroll
;         for (int bj = 0; bj < 2; ++bj)
; #pragma unroll
;             for (int n = 0; n < 2; ++n) bv[bj][n] = *(const f32x4*)(bias + col0 + bj * 128 + 4 * n);
; #pragma unroll
;         for (int ai = 0; ai < 2; ++ai)
; #pragma unroll
;             for (int m = 0; m < 4; ++m) { bf16_t* rowp = a1 + (size_t)(row0 + ai * 128 + m * 16) * DFF + col0;
; #pragma unroll
;                 for (int bj = 0; bj < 2; ++bj) { f32x4 v0 = acc[ai][bj][m][0] + bv[bj][0], v1 = acc[ai][bj][m][1] + bv[bj][1];
; #pragma unroll
;                     for (int j = 0; j < 4; ++j) { const float a = fmaxf(v0[j], 0.f), b = fmaxf(v1[j], 0.f); v0[j] = a * a; v1[j] = b * b; }
;                     u32x4 w; w.x = pk2(v0[0], v0[1]); w.y = pk2(v0[2], v0[3]); w.z = pk2(v1[0], v1[1]); w.w = pk2(v1[2], v1[3]);
;                     *(u32x4*)(rowp + bj * 128) = w; } }
.LBB0_850:
	v_mov_b32_e32 v145, 0
	v_mov_b32_e32 v144, v145
	v_mov_b32_e32 v143, v145
	v_mov_b32_e32 v142, v145
	v_mov_b32_e32 v141, v145
	v_mov_b32_e32 v140, v145
	v_mov_b32_e32 v139, v145
	v_mov_b32_e32 v138, v145
	v_mov_b32_e32 v113, v145
	v_mov_b32_e32 v112, v145
	v_mov_b32_e32 v111, v145
	v_mov_b32_e32 v110, v145
	v_mov_b32_e32 v109, v145
	v_mov_b32_e32 v108, v145
	v_mov_b32_e32 v107, v145
	v_mov_b32_e32 v106, v145
	v_mov_b32_e32 v97, v145
	v_mov_b32_e32 v96, v145
	v_mov_b32_e32 v95, v145
	v_mov_b32_e32 v94, v145
	v_mov_b32_e32 v93, v145
	v_mov_b32_e32 v92, v145
	v_mov_b32_e32 v91, v145
	v_mov_b32_e32 v90, v145
	v_mov_b32_e32 v81, v145
	v_mov_b32_e32 v80, v145
	v_mov_b32_e32 v79, v145
	v_mov_b32_e32 v78, v145
	v_mov_b32_e32 v77, v145
	v_mov_b32_e32 v76, v145
	v_mov_b32_e32 v75, v145
	v_mov_b32_e32 v74, v145
	v_mov_b32_e32 v137, v145
	v_mov_b32_e32 v136, v145
	v_mov_b32_e32 v135, v145
	v_mov_b32_e32 v134, v145
	v_mov_b32_e32 v133, v145
	v_mov_b32_e32 v132, v145
	v_mov_b32_e32 v131, v145
	v_mov_b32_e32 v130, v145
	v_mov_b32_e32 v105, v145
	v_mov_b32_e32 v104, v145
	v_mov_b32_e32 v103, v145
	v_mov_b32_e32 v102, v145
	v_mov_b32_e32 v101, v145
	v_mov_b32_e32 v100, v145
	v_mov_b32_e32 v99, v145
	v_mov_b32_e32 v98, v145
	v_mov_b32_e32 v89, v145
	v_mov_b32_e32 v88, v145
	v_mov_b32_e32 v87, v145
	v_mov_b32_e32 v86, v145
	v_mov_b32_e32 v85, v145
	v_mov_b32_e32 v84, v145
	v_mov_b32_e32 v83, v145
	v_mov_b32_e32 v82, v145
	v_mov_b32_e32 v73, v145
	v_mov_b32_e32 v72, v145
	v_mov_b32_e32 v71, v145
	v_mov_b32_e32 v70, v145
	v_mov_b32_e32 v69, v145
	v_mov_b32_e32 v68, v145
	v_mov_b32_e32 v67, v145
	v_mov_b32_e32 v66, v145
	v_mov_b32_e32 v63, v145
	v_mov_b32_e32 v62, v145
	v_mov_b32_e32 v61, v145
	v_mov_b32_e32 v60, v145
	v_mov_b32_e32 v59, v145
	v_mov_b32_e32 v58, v145
	v_mov_b32_e32 v57, v145
	v_mov_b32_e32 v56, v145
	v_mov_b32_e32 v47, v145
	v_mov_b32_e32 v46, v145
	v_mov_b32_e32 v45, v145
	v_mov_b32_e32 v44, v145
	v_mov_b32_e32 v43, v145
	v_mov_b32_e32 v42, v145
	v_mov_b32_e32 v41, v145
	v_mov_b32_e32 v40, v145
	v_mov_b32_e32 v31, v145
	v_mov_b32_e32 v30, v145
	v_mov_b32_e32 v29, v145
	v_mov_b32_e32 v28, v145
	v_mov_b32_e32 v27, v145
	v_mov_b32_e32 v26, v145
	v_mov_b32_e32 v25, v145
	v_mov_b32_e32 v24, v145
	v_mov_b32_e32 v15, v145
	v_mov_b32_e32 v14, v145
	v_mov_b32_e32 v13, v145
	v_mov_b32_e32 v12, v145
	v_mov_b32_e32 v11, v145
	v_mov_b32_e32 v10, v145
	v_mov_b32_e32 v9, v145
	v_mov_b32_e32 v8, v145
	v_mov_b32_e32 v55, v145
	v_mov_b32_e32 v54, v145
	v_mov_b32_e32 v53, v145
	v_mov_b32_e32 v52, v145
	v_mov_b32_e32 v51, v145
	v_mov_b32_e32 v50, v145
	v_mov_b32_e32 v49, v145
	v_mov_b32_e32 v48, v145
	v_mov_b32_e32 v39, v145
	v_mov_b32_e32 v38, v145
	v_mov_b32_e32 v37, v145
	v_mov_b32_e32 v36, v145
	v_mov_b32_e32 v35, v145
	v_mov_b32_e32 v34, v145
	v_mov_b32_e32 v33, v145
	v_mov_b32_e32 v32, v145
	v_mov_b32_e32 v23, v145
	v_mov_b32_e32 v22, v145
	v_mov_b32_e32 v21, v145
	v_mov_b32_e32 v20, v145
	v_mov_b32_e32 v19, v145
	v_mov_b32_e32 v18, v145
	v_mov_b32_e32 v17, v145
	v_mov_b32_e32 v16, v145
	v_mov_b32_e32 v7, v145
	v_mov_b32_e32 v6, v145
	v_mov_b32_e32 v5, v145
	v_mov_b32_e32 v4, v145
	v_mov_b32_e32 v3, v145
	v_mov_b32_e32 v2, v145
	v_mov_b32_e32 v1, v145
	v_mov_b32_e32 v0, v145
	v_lshl_or_b32 v252, s34, 8, v172
	v_ashrrev_i32_e32 v253, 31, v252
	v_lshl_add_u64 v[252:253], v[252:253], 2, s[18:19]
	global_load_dwordx4 v[240:243], v[252:253], off
	global_load_dwordx4 v[244:247], v[252:253], off offset:16
	global_load_dwordx4 v[248:251], v[252:253], off offset:512
	global_load_dwordx4 v[252:255], v[252:253], off offset:528
	s_waitcnt vmcnt(0)
.LBB0_851:
	v_bfe_u32 v156, v194, 8, 1
	v_lshlrev_b32_e32 v156, 4, v156
	v_and_b32_e32 v157, 15, v194
	v_add_u32_e32 v156, v156, v157
	v_mul_u32_u24_e32 v186, 0x110, v156
	v_bfe_u32 v158, v194, 6, 2
	v_bfe_u32 v159, v194, 4, 2
	v_lshl_add_u32 v186, v158, 6, v186
	v_lshl_add_u32 v186, v159, 4, v186
	v_add_u32_e32 v186, 0x23410, v186
	v_lshrrev_b32_e32 v160, 6, v194
	v_lshl_add_u32 v160, v160, 2, v159
	v_mul_u32_u24_e32 v187, 0x110, v160
	v_lshl_add_u32 v187, v157, 4, v187
	v_add_u32_e32 v187, 0x23410, v187
	v_bfe_u32 v156, v194, 8, 1
	v_lshlrev_b32_e32 v156, 6, v156
	v_lshl_add_u32 v156, v158, 2, v156
	v_add_u32_e32 v156, v156, v159
	v_lshl_add_u32 v160, s30, 8, v156
	v_mov_b32_e32 v161, 0
	v_lshlrev_b64 v[160:161], 14, v[160:161]
	v_lshlrev_b32_e32 v158, 4, v157
	v_lshl_add_u32 v158, s34, 9, v158
	v_mov_b32_e32 v159, 0
	v_lshl_add_u64 v[188:189], s[14:15], 0, v[160:161]
	v_lshl_add_u64 v[188:189], v[188:189], 0, v[158:159]
	s_mov_b32 s21, 0x200000
	s_mov_b64 s[36:37], 0x200000
	s_mov_b32 s62, s61
	s_mov_b32 s34, s20
	s_mov_b32 s30, s22
	s_mov_b64 s[38:39], s[28:29]
	s_mov_b32 s99, 0
	s_waitcnt vmcnt(6)
	v_pk_add_f32 v[142:143], v[142:143], v[240:241]
	v_pk_add_f32 v[144:145], v[144:145], v[242:243]
	v_max_f32_e32 v142, 0, v142
	v_max_f32_e32 v143, 0, v143
	v_max_f32_e32 v144, 0, v144
	v_max_f32_e32 v145, 0, v145
	v_pk_mul_f32 v[142:143], v[142:143], v[142:143]
	v_pk_mul_f32 v[144:145], v[144:145], v[144:145]
	v_pk_add_f32 v[138:139], v[138:139], v[244:245]
	v_pk_add_f32 v[140:141], v[140:141], v[246:247]
	v_max_f32_e32 v138, 0, v138
	v_max_f32_e32 v139, 0, v139
	v_max_f32_e32 v140, 0, v140
	v_max_f32_e32 v141, 0, v141
	v_pk_mul_f32 v[138:139], v[138:139], v[138:139]
	v_pk_mul_f32 v[140:141], v[140:141], v[140:141]
	v_cvt_pk_bf16_f32 v174, v142, v143
	v_cvt_pk_bf16_f32 v175, v144, v145
	v_cvt_pk_bf16_f32 v176, v138, v139
	v_cvt_pk_bf16_f32 v177, v140, v141
	ds_write_b128 v186, v[174:177]
	s_waitcnt lgkmcnt(0)
	s_barrier
; __device__ __forceinline__ unsigned pk2(float lo, float hi) { const v2f_t f = {lo, hi}; const v2bf_t b = __builtin_convertvector(f, v2bf_t); return __builtin_bit_cast(unsigned, b); }
;     __device__ __forceinline__ void operator()(const f32x4 (&acc)[2][2][4][2], const Unit& u, int wr, int wc, int fr, int fq) const {
;     ...
; #pragma unroll
;         for (int ai = 0; ai < 2; ++ai)
; #pragma unroll
;             for (int m = 0; m < 4; ++m) { bf16_t* rowp = a1 + (size_t)(row0 + ai * 128 + m * 16) * DFF + col0;
; #pragma unroll
;                 for (int bj = 0; bj < 2; ++bj) { f32x4 v0 = acc[ai][bj][m][0] + bv[bj][0], v1 = acc[ai][bj][m][1] + bv[bj][1];
; #pragma unroll
;                     for (int j = 0; j < 4; ++j) { const float a = fmaxf(v0[j], 0.f), b = fmaxf(v1[j], 0.f); v0[j] = a * a; v1[j] = b * b; }
;                     u32x4 w; w.x = pk2(v0[0], v0[1]); w.y = pk2(v0[2], v0[3]); w.z = pk2(v1[0], v1[1]); w.w = pk2(v1[2], v1[3]);
;                     *(u32x4*)(rowp + bj * 128) = w; } }
	ds_read_b128 v[178:181], v187
	s_mov_b32 s98, 0x0
	v_lshl_add_u64 v[190:191], v[188:189], 0, s[98:99]
	v_pk_add_f32 v[134:135], v[134:135], v[248:249]
	v_pk_add_f32 v[136:137], v[136:137], v[250:251]
	v_max_f32_e32 v134, 0, v134
	v_max_f32_e32 v135, 0, v135
	v_max_f32_e32 v136, 0, v136
	v_max_f32_e32 v137, 0, v137
	v_pk_mul_f32 v[134:135], v[134:135], v[134:135]
	v_pk_mul_f32 v[136:137], v[136:137], v[136:137]
	v_pk_add_f32 v[130:131], v[130:131], v[252:253]
	v_pk_add_f32 v[132:133], v[132:133], v[254:255]
	v_max_f32_e32 v130, 0, v130
	v_max_f32_e32 v131, 0, v131
	v_max_f32_e32 v132, 0, v132
	v_max_f32_e32 v133, 0, v133
	v_pk_mul_f32 v[130:131], v[130:131], v[130:131]
	v_pk_mul_f32 v[132:133], v[132:133], v[132:133]
	v_cvt_pk_bf16_f32 v174, v134, v135
	v_cvt_pk_bf16_f32 v175, v136, v137
	v_cvt_pk_bf16_f32 v176, v130, v131
	v_cvt_pk_bf16_f32 v177, v132, v133
	ds_write_b128 v186, v[174:177] offset:8704
	s_waitcnt lgkmcnt(1)
	global_store_dwordx4 v[190:191], v[178:181], off
	s_waitcnt lgkmcnt(0)
	s_barrier
	ds_read_b128 v[182:185], v187 offset:8704
	v_pk_add_f32 v[110:111], v[110:111], v[240:241]
	v_pk_add_f32 v[112:113], v[112:113], v[242:243]
	v_max_f32_e32 v110, 0, v110
	v_max_f32_e32 v111, 0, v111
	v_max_f32_e32 v112, 0, v112
	v_max_f32_e32 v113, 0, v113
	v_pk_mul_f32 v[110:111], v[110:111], v[110:111]
	v_pk_mul_f32 v[112:113], v[112:113], v[112:113]
	v_pk_add_f32 v[106:107], v[106:107], v[244:245]
	v_pk_add_f32 v[108:109], v[108:109], v[246:247]
	v_max_f32_e32 v106, 0, v106
	v_max_f32_e32 v107, 0, v107
	v_max_f32_e32 v108, 0, v108
	v_max_f32_e32 v109, 0, v109
	v_pk_mul_f32 v[106:107], v[106:107], v[106:107]
	v_pk_mul_f32 v[108:109], v[108:109], v[108:109]
	v_cvt_pk_bf16_f32 v174, v110, v111
	v_cvt_pk_bf16_f32 v175, v112, v113
	v_cvt_pk_bf16_f32 v176, v106, v107
	v_cvt_pk_bf16_f32 v177, v108, v109
	ds_write_b128 v186, v[174:177]
	s_waitcnt lgkmcnt(1)
	global_store_dwordx4 v[190:191], v[182:185], off offset:256
	s_waitcnt lgkmcnt(0)
	s_barrier
	ds_read_b128 v[178:181], v187
	s_mov_b32 s98, 0x40000
	v_lshl_add_u64 v[190:191], v[188:189], 0, s[98:99]
	v_pk_add_f32 v[102:103], v[102:103], v[248:249]
	v_pk_add_f32 v[104:105], v[104:105], v[250:251]
	v_max_f32_e32 v102, 0, v102
	v_max_f32_e32 v103, 0, v103
	v_max_f32_e32 v104, 0, v104
	v_max_f32_e32 v105, 0, v105
	v_pk_mul_f32 v[102:103], v[102:103], v[102:103]
	v_pk_mul_f32 v[104:105], v[104:105], v[104:105]
	v_pk_add_f32 v[98:99], v[98:99], v[252:253]
	v_pk_add_f32 v[100:101], v[100:101], v[254:255]
	v_max_f32_e32 v98, 0, v98
	v_max_f32_e32 v99, 0, v99
	v_max_f32_e32 v100, 0, v100
	v_max_f32_e32 v101, 0, v101
	v_pk_mul_f32 v[98:99], v[98:99], v[98:99]
	v_pk_mul_f32 v[100:101], v[100:101], v[100:101]
	v_cvt_pk_bf16_f32 v174, v102, v103
	v_cvt_pk_bf16_f32 v175, v104, v105
	v_cvt_pk_bf16_f32 v176, v98, v99
	v_cvt_pk_bf16_f32 v177, v100, v101
	ds_write_b128 v186, v[174:177] offset:8704
	s_waitcnt lgkmcnt(1)
	global_store_dwordx4 v[190:191], v[178:181], off
	s_waitcnt lgkmcnt(0)
	s_barrier
	ds_read_b128 v[182:185], v187 offset:8704
	v_pk_add_f32 v[94:95], v[94:95], v[240:241]
	v_pk_add_f32 v[96:97], v[96:97], v[242:243]
	v_max_f32_e32 v94, 0, v94
	v_max_f32_e32 v95, 0, v95
	v_max_f32_e32 v96, 0, v96
	v_max_f32_e32 v97, 0, v97
	v_pk_mul_f32 v[94:95], v[94:95], v[94:95]
	v_pk_mul_f32 v[96:97], v[96:97], v[96:97]
	v_pk_add_f32 v[90:91], v[90:91], v[244:245]
	v_pk_add_f32 v[92:93], v[92:93], v[246:247]
	v_max_f32_e32 v90, 0, v90
	v_max_f32_e32 v91, 0, v91
	v_max_f32_e32 v92, 0, v92
	v_max_f32_e32 v93, 0, v93
	v_pk_mul_f32 v[90:91], v[90:91], v[90:91]
	v_pk_mul_f32 v[92:93], v[92:93], v[92:93]
	v_cvt_pk_bf16_f32 v174, v94, v95
	v_cvt_pk_bf16_f32 v175, v96, v97
	v_cvt_pk_bf16_f32 v176, v90, v91
	v_cvt_pk_bf16_f32 v177, v92, v93
	ds_write_b128 v186, v[174:177]
	s_waitcnt lgkmcnt(1)
	global_store_dwordx4 v[190:191], v[182:185], off offset:256
	s_waitcnt lgkmcnt(0)
	s_barrier
	ds_read_b128 v[178:181], v187
	s_mov_b32 s98, 0x80000
	v_lshl_add_u64 v[190:191], v[188:189], 0, s[98:99]
	v_pk_add_f32 v[86:87], v[86:87], v[248:249]
	v_pk_add_f32 v[88:89], v[88:89], v[250:251]
	v_max_f32_e32 v86, 0, v86
	v_max_f32_e32 v87, 0, v87
	v_max_f32_e32 v88, 0, v88
	v_max_f32_e32 v89, 0, v89
	v_pk_mul_f32 v[86:87], v[86:87], v[86:87]
	v_pk_mul_f32 v[88:89], v[88:89], v[88:89]
	v_pk_add_f32 v[82:83], v[82:83], v[252:253]
	v_pk_add_f32 v[84:85], v[84:85], v[254:255]
	v_max_f32_e32 v82, 0, v82
	v_max_f32_e32 v83, 0, v83
	v_max_f32_e32 v84, 0, v84
	v_max_f32_e32 v85, 0, v85
	v_pk_mul_f32 v[82:83], v[82:83], v[82:83]
	v_pk_mul_f32 v[84:85], v[84:85], v[84:85]
	v_cvt_pk_bf16_f32 v174, v86, v87
	v_cvt_pk_bf16_f32 v175, v88, v89
	v_cvt_pk_bf16_f32 v176, v82, v83
	v_cvt_pk_bf16_f32 v177, v84, v85
	ds_write_b128 v186, v[174:177] offset:8704
	s_waitcnt lgkmcnt(1)
	global_store_dwordx4 v[190:191], v[178:181], off
	s_waitcnt lgkmcnt(0)
	s_barrier
	ds_read_b128 v[182:185], v187 offset:8704
	v_pk_add_f32 v[78:79], v[78:79], v[240:241]
	v_pk_add_f32 v[80:81], v[80:81], v[242:243]
	v_max_f32_e32 v78, 0, v78
	v_max_f32_e32 v79, 0, v79
	v_max_f32_e32 v80, 0, v80
	v_max_f32_e32 v81, 0, v81
	v_pk_mul_f32 v[78:79], v[78:79], v[78:79]
	v_pk_mul_f32 v[80:81], v[80:81], v[80:81]
	v_pk_add_f32 v[74:75], v[74:75], v[244:245]
	v_pk_add_f32 v[76:77], v[76:77], v[246:247]
	v_max_f32_e32 v74, 0, v74
	v_max_f32_e32 v75, 0, v75
	v_max_f32_e32 v76, 0, v76
	v_max_f32_e32 v77, 0, v77
	v_pk_mul_f32 v[74:75], v[74:75], v[74:75]
	v_pk_mul_f32 v[76:77], v[76:77], v[76:77]
	v_cvt_pk_bf16_f32 v174, v78, v79
	v_cvt_pk_bf16_f32 v175, v80, v81
	v_cvt_pk_bf16_f32 v176, v74, v75
	v_cvt_pk_bf16_f32 v177, v76, v77
	ds_write_b128 v186, v[174:177]
	s_waitcnt lgkmcnt(1)
	global_store_dwordx4 v[190:191], v[182:185], off offset:256
	s_waitcnt lgkmcnt(0)
	s_barrier
; __device__ __forceinline__ unsigned pk2(float lo, float hi) { const v2f_t f = {lo, hi}; const v2bf_t b = __builtin_convertvector(f, v2bf_t); return __builtin_bit_cast(unsigned, b); }
;     __device__ __forceinline__ void operator()(const f32x4 (&acc)[2][2][4][2], const Unit& u, int wr, int wc, int fr, int fq) const {
;     ...
; #pragma unroll
;         for (int ai = 0; ai < 2; ++ai)
; #pragma unroll
;             for (int m = 0; m < 4; ++m) { bf16_t* rowp = a1 + (size_t)(row0 + ai * 128 + m * 16) * DFF + col0;
; #pragma unroll
;                 for (int bj = 0; bj < 2; ++bj) { f32x4 v0 = acc[ai][bj][m][0] + bv[bj][0], v1 = acc[ai][bj][m][1] + bv[bj][1];
; #pragma unroll
;                     for (int j = 0; j < 4; ++j) { const float a = fmaxf(v0[j], 0.f), b = fmaxf(v1[j], 0.f); v0[j] = a * a; v1[j] = b * b; }
;                     u32x4 w; w.x = pk2(v0[0], v0[1]); w.y = pk2(v0[2], v0[3]); w.z = pk2(v1[0], v1[1]); w.w = pk2(v1[2], v1[3]);
;                     *(u32x4*)(rowp + bj * 128) = w; } }
	ds_read_b128 v[178:181], v187
	s_mov_b32 s98, 0xc0000
	v_lshl_add_u64 v[190:191], v[188:189], 0, s[98:99]
	v_pk_add_f32 v[70:71], v[70:71], v[248:249]
	v_pk_add_f32 v[72:73], v[72:73], v[250:251]
	v_max_f32_e32 v70, 0, v70
	v_max_f32_e32 v71, 0, v71
	v_max_f32_e32 v72, 0, v72
	v_max_f32_e32 v73, 0, v73
	v_pk_mul_f32 v[70:71], v[70:71], v[70:71]
	v_pk_mul_f32 v[72:73], v[72:73], v[72:73]
	v_pk_add_f32 v[66:67], v[66:67], v[252:253]
	v_pk_add_f32 v[68:69], v[68:69], v[254:255]
	v_max_f32_e32 v66, 0, v66
	v_max_f32_e32 v67, 0, v67
	v_max_f32_e32 v68, 0, v68
	v_max_f32_e32 v69, 0, v69
	v_pk_mul_f32 v[66:67], v[66:67], v[66:67]
	v_pk_mul_f32 v[68:69], v[68:69], v[68:69]
	v_cvt_pk_bf16_f32 v174, v70, v71
	v_cvt_pk_bf16_f32 v175, v72, v73
	v_cvt_pk_bf16_f32 v176, v66, v67
	v_cvt_pk_bf16_f32 v177, v68, v69
	ds_write_b128 v186, v[174:177] offset:8704
	s_waitcnt lgkmcnt(1)
	global_store_dwordx4 v[190:191], v[178:181], off
	s_waitcnt lgkmcnt(0)
	s_barrier
	ds_read_b128 v[182:185], v187 offset:8704
	v_pk_add_f32 v[60:61], v[60:61], v[240:241]
	v_pk_add_f32 v[62:63], v[62:63], v[242:243]
	v_max_f32_e32 v60, 0, v60
	v_max_f32_e32 v61, 0, v61
	v_max_f32_e32 v62, 0, v62
	v_max_f32_e32 v63, 0, v63
	v_pk_mul_f32 v[60:61], v[60:61], v[60:61]
	v_pk_mul_f32 v[62:63], v[62:63], v[62:63]
	v_pk_add_f32 v[56:57], v[56:57], v[244:245]
	v_pk_add_f32 v[58:59], v[58:59], v[246:247]
	v_max_f32_e32 v56, 0, v56
	v_max_f32_e32 v57, 0, v57
	v_max_f32_e32 v58, 0, v58
	v_max_f32_e32 v59, 0, v59
	v_pk_mul_f32 v[56:57], v[56:57], v[56:57]
	v_pk_mul_f32 v[58:59], v[58:59], v[58:59]
	v_cvt_pk_bf16_f32 v174, v60, v61
	v_cvt_pk_bf16_f32 v175, v62, v63
	v_cvt_pk_bf16_f32 v176, v56, v57
	v_cvt_pk_bf16_f32 v177, v58, v59
	ds_write_b128 v186, v[174:177]
	s_waitcnt lgkmcnt(1)
	global_store_dwordx4 v[190:191], v[182:185], off offset:256
	s_waitcnt lgkmcnt(0)
	s_barrier
	ds_read_b128 v[178:181], v187
	s_mov_b32 s98, 0x200000
	v_lshl_add_u64 v[190:191], v[188:189], 0, s[98:99]
	v_pk_add_f32 v[52:53], v[52:53], v[248:249]
	v_pk_add_f32 v[54:55], v[54:55], v[250:251]
	v_max_f32_e32 v52, 0, v52
	v_max_f32_e32 v53, 0, v53
	v_max_f32_e32 v54, 0, v54
	v_max_f32_e32 v55, 0, v55
	v_pk_mul_f32 v[52:53], v[52:53], v[52:53]
	v_pk_mul_f32 v[54:55], v[54:55], v[54:55]
	v_pk_add_f32 v[48:49], v[48:49], v[252:253]
	v_pk_add_f32 v[50:51], v[50:51], v[254:255]
	v_max_f32_e32 v48, 0, v48
	v_max_f32_e32 v49, 0, v49
	v_max_f32_e32 v50, 0, v50
	v_max_f32_e32 v51, 0, v51
	v_pk_mul_f32 v[48:49], v[48:49], v[48:49]
	v_pk_mul_f32 v[50:51], v[50:51], v[50:51]
	v_cvt_pk_bf16_f32 v174, v52, v53
	v_cvt_pk_bf16_f32 v175, v54, v55
	v_cvt_pk_bf16_f32 v176, v48, v49
	v_cvt_pk_bf16_f32 v177, v50, v51
	ds_write_b128 v186, v[174:177] offset:8704
	s_waitcnt lgkmcnt(1)
	global_store_dwordx4 v[190:191], v[178:181], off
	s_waitcnt lgkmcnt(0)
	s_barrier
	ds_read_b128 v[182:185], v187 offset:8704
	v_pk_add_f32 v[44:45], v[44:45], v[240:241]
	v_pk_add_f32 v[46:47], v[46:47], v[242:243]
	v_max_f32_e32 v44, 0, v44
	v_max_f32_e32 v45, 0, v45
	v_max_f32_e32 v46, 0, v46
	v_max_f32_e32 v47, 0, v47
	v_pk_mul_f32 v[44:45], v[44:45], v[44:45]
	v_pk_mul_f32 v[46:47], v[46:47], v[46:47]
	v_pk_add_f32 v[40:41], v[40:41], v[244:245]
	v_pk_add_f32 v[42:43], v[42:43], v[246:247]
	v_max_f32_e32 v40, 0, v40
	v_max_f32_e32 v41, 0, v41
	v_max_f32_e32 v42, 0, v42
	v_max_f32_e32 v43, 0, v43
	v_pk_mul_f32 v[40:41], v[40:41], v[40:41]
	v_pk_mul_f32 v[42:43], v[42:43], v[42:43]
	v_cvt_pk_bf16_f32 v174, v44, v45
	v_cvt_pk_bf16_f32 v175, v46, v47
	v_cvt_pk_bf16_f32 v176, v40, v41
	v_cvt_pk_bf16_f32 v177, v42, v43
	ds_write_b128 v186, v[174:177]
	s_waitcnt lgkmcnt(1)
	global_store_dwordx4 v[190:191], v[182:185], off offset:256
	s_waitcnt lgkmcnt(0)
	s_barrier
	ds_read_b128 v[178:181], v187
	s_mov_b32 s98, 0x240000
	v_lshl_add_u64 v[190:191], v[188:189], 0, s[98:99]
	v_pk_add_f32 v[36:37], v[36:37], v[248:249]
	v_pk_add_f32 v[38:39], v[38:39], v[250:251]
	v_max_f32_e32 v36, 0, v36
	v_max_f32_e32 v37, 0, v37
	v_max_f32_e32 v38, 0, v38
	v_max_f32_e32 v39, 0, v39
	v_pk_mul_f32 v[36:37], v[36:37], v[36:37]
	v_pk_mul_f32 v[38:39], v[38:39], v[38:39]
	v_pk_add_f32 v[32:33], v[32:33], v[252:253]
	v_pk_add_f32 v[34:35], v[34:35], v[254:255]
	v_max_f32_e32 v32, 0, v32
	v_max_f32_e32 v33, 0, v33
	v_max_f32_e32 v34, 0, v34
	v_max_f32_e32 v35, 0, v35
	v_pk_mul_f32 v[32:33], v[32:33], v[32:33]
	v_pk_mul_f32 v[34:35], v[34:35], v[34:35]
	v_cvt_pk_bf16_f32 v174, v36, v37
	v_cvt_pk_bf16_f32 v175, v38, v39
	v_cvt_pk_bf16_f32 v176, v32, v33
	v_cvt_pk_bf16_f32 v177, v34, v35
	ds_write_b128 v186, v[174:177] offset:8704
	s_waitcnt lgkmcnt(1)
	global_store_dwordx4 v[190:191], v[178:181], off
	s_waitcnt lgkmcnt(0)
	s_barrier
; __device__ __forceinline__ unsigned pk2(float lo, float hi) { const v2f_t f = {lo, hi}; const v2bf_t b = __builtin_convertvector(f, v2bf_t); return __builtin_bit_cast(unsigned, b); }
;     __device__ __forceinline__ void operator()(const f32x4 (&acc)[2][2][4][2], const Unit& u, int wr, int wc, int fr, int fq) const {
;     ...
; #pragma unroll
;         for (int ai = 0; ai < 2; ++ai)
; #pragma unroll
;             for (int m = 0; m < 4; ++m) { bf16_t* rowp = a1 + (size_t)(row0 + ai * 128 + m * 16) * DFF + col0;
; #pragma unroll
;                 for (int bj = 0; bj < 2; ++bj) { f32x4 v0 = acc[ai][bj][m][0] + bv[bj][0], v1 = acc[ai][bj][m][1] + bv[bj][1];
; #pragma unroll
;                     for (int j = 0; j < 4; ++j) { const float a = fmaxf(v0[j], 0.f), b = fmaxf(v1[j], 0.f); v0[j] = a * a; v1[j] = b * b; }
;                     u32x4 w; w.x = pk2(v0[0], v0[1]); w.y = pk2(v0[2], v0[3]); w.z = pk2(v1[0], v1[1]); w.w = pk2(v1[2], v1[3]);
;                     *(u32x4*)(rowp + bj * 128) = w; } }
	ds_read_b128 v[182:185], v187 offset:8704
	v_pk_add_f32 v[28:29], v[28:29], v[240:241]
	v_pk_add_f32 v[30:31], v[30:31], v[242:243]
	v_max_f32_e32 v28, 0, v28
	v_max_f32_e32 v29, 0, v29
	v_max_f32_e32 v30, 0, v30
	v_max_f32_e32 v31, 0, v31
	v_pk_mul_f32 v[28:29], v[28:29], v[28:29]
	v_pk_mul_f32 v[30:31], v[30:31], v[30:31]
	v_pk_add_f32 v[24:25], v[24:25], v[244:245]
	v_pk_add_f32 v[26:27], v[26:27], v[246:247]
	v_max_f32_e32 v24, 0, v24
	v_max_f32_e32 v25, 0, v25
	v_max_f32_e32 v26, 0, v26
	v_max_f32_e32 v27, 0, v27
	v_pk_mul_f32 v[24:25], v[24:25], v[24:25]
	v_pk_mul_f32 v[26:27], v[26:27], v[26:27]
	v_cvt_pk_bf16_f32 v174, v28, v29
	v_cvt_pk_bf16_f32 v175, v30, v31
	v_cvt_pk_bf16_f32 v176, v24, v25
	v_cvt_pk_bf16_f32 v177, v26, v27
	ds_write_b128 v186, v[174:177]
	s_waitcnt lgkmcnt(1)
	global_store_dwordx4 v[190:191], v[182:185], off offset:256
	s_waitcnt lgkmcnt(0)
	s_barrier
	ds_read_b128 v[178:181], v187
	s_mov_b32 s98, 0x280000
	v_lshl_add_u64 v[190:191], v[188:189], 0, s[98:99]
	v_pk_add_f32 v[20:21], v[20:21], v[248:249]
	v_pk_add_f32 v[22:23], v[22:23], v[250:251]
	v_max_f32_e32 v20, 0, v20
	v_max_f32_e32 v21, 0, v21
	v_max_f32_e32 v22, 0, v22
	v_max_f32_e32 v23, 0, v23
	v_pk_mul_f32 v[20:21], v[20:21], v[20:21]
	v_pk_mul_f32 v[22:23], v[22:23], v[22:23]
	v_pk_add_f32 v[16:17], v[16:17], v[252:253]
	v_pk_add_f32 v[18:19], v[18:19], v[254:255]
	v_max_f32_e32 v16, 0, v16
	v_max_f32_e32 v17, 0, v17
	v_max_f32_e32 v18, 0, v18
	v_max_f32_e32 v19, 0, v19
	v_pk_mul_f32 v[16:17], v[16:17], v[16:17]
	v_pk_mul_f32 v[18:19], v[18:19], v[18:19]
	v_cvt_pk_bf16_f32 v174, v20, v21
	v_cvt_pk_bf16_f32 v175, v22, v23
	v_cvt_pk_bf16_f32 v176, v16, v17
	v_cvt_pk_bf16_f32 v177, v18, v19
	ds_write_b128 v186, v[174:177] offset:8704
	s_waitcnt lgkmcnt(1)
	global_store_dwordx4 v[190:191], v[178:181], off
	s_waitcnt lgkmcnt(0)
	s_barrier
	ds_read_b128 v[182:185], v187 offset:8704
	v_pk_add_f32 v[12:13], v[12:13], v[240:241]
	v_pk_add_f32 v[14:15], v[14:15], v[242:243]
	v_max_f32_e32 v12, 0, v12
	v_max_f32_e32 v13, 0, v13
	v_max_f32_e32 v14, 0, v14
	v_max_f32_e32 v15, 0, v15
	v_pk_mul_f32 v[12:13], v[12:13], v[12:13]
	v_pk_mul_f32 v[14:15], v[14:15], v[14:15]
	v_pk_add_f32 v[8:9], v[8:9], v[244:245]
	v_pk_add_f32 v[10:11], v[10:11], v[246:247]
	v_max_f32_e32 v8, 0, v8
	v_max_f32_e32 v9, 0, v9
	v_max_f32_e32 v10, 0, v10
	v_max_f32_e32 v11, 0, v11
	v_pk_mul_f32 v[8:9], v[8:9], v[8:9]
	v_pk_mul_f32 v[10:11], v[10:11], v[10:11]
	v_cvt_pk_bf16_f32 v174, v12, v13
	v_cvt_pk_bf16_f32 v175, v14, v15
	v_cvt_pk_bf16_f32 v176, v8, v9
	v_cvt_pk_bf16_f32 v177, v10, v11
	ds_write_b128 v186, v[174:177]
	s_waitcnt lgkmcnt(1)
	global_store_dwordx4 v[190:191], v[182:185], off offset:256
	s_waitcnt lgkmcnt(0)
	s_barrier
	ds_read_b128 v[178:181], v187
	s_mov_b32 s98, 0x2c0000
	v_lshl_add_u64 v[190:191], v[188:189], 0, s[98:99]
	v_pk_add_f32 v[4:5], v[4:5], v[248:249]
	v_pk_add_f32 v[6:7], v[6:7], v[250:251]
	v_max_f32_e32 v4, 0, v4
	v_max_f32_e32 v5, 0, v5
	v_max_f32_e32 v6, 0, v6
	v_max_f32_e32 v7, 0, v7
	v_pk_mul_f32 v[4:5], v[4:5], v[4:5]
	v_pk_mul_f32 v[6:7], v[6:7], v[6:7]
	v_pk_add_f32 v[0:1], v[0:1], v[252:253]
	v_pk_add_f32 v[2:3], v[2:3], v[254:255]
	v_max_f32_e32 v0, 0, v0
	v_max_f32_e32 v1, 0, v1
	v_max_f32_e32 v2, 0, v2
	v_max_f32_e32 v3, 0, v3
	v_pk_mul_f32 v[0:1], v[0:1], v[0:1]
	v_pk_mul_f32 v[2:3], v[2:3], v[2:3]
	v_cvt_pk_bf16_f32 v174, v4, v5
	v_cvt_pk_bf16_f32 v175, v6, v7
	v_cvt_pk_bf16_f32 v176, v0, v1
	v_cvt_pk_bf16_f32 v177, v2, v3
	ds_write_b128 v186, v[174:177] offset:8704
	s_waitcnt lgkmcnt(1)
	global_store_dwordx4 v[190:191], v[178:181], off
	s_waitcnt lgkmcnt(0)
	s_barrier
	ds_read_b128 v[182:185], v187 offset:8704
	s_waitcnt lgkmcnt(0)
	global_store_dwordx4 v[190:191], v[182:185], off offset:256
	s_and_b64 vcc, exec, s[26:27]
	s_mov_b64 s[36:37], s[24:25]
	s_cbranch_vccnz .LBB0_861

; #define PG8_STAGE(bufoff, gbase, voff) do { _Pragma("unroll") for (int _i = 0; _i < 2; ++_i) \
;         __builtin_amdgcn_global_load_lds((const unsigned*)((const char*)(gbase) + (voff)[_i]), (LAS unsigned*)(lds + (bufoff) + ldsw + _i * 8192), 16, 0, 0); } while (0)
; #define PG8_WAIT_V(n) asm volatile("s_waitcnt vmcnt(" #n ")" ::: "memory")
; #define PG8_BAR __builtin_amdgcn_s_barrier()
; template <class Epi>
; __device__ __forceinline__ void gemm_phase(LAS unsigned char* lds, const Gemm g, StaticOrder S, const Epi& E) {
;     ...
;     const char* cA = (const char*)g.A + (size_t)cur.pm * tstepA + (size_t)cur.pn * g.a_pn_off + (size_t)cur.kt0 * kstep; const char* cB = (const char*)g.Bt + (size_t)cur.pn * tstepB + (size_t)cur.kt0 * kstep;
;     PG8_STAGE(PG8_SB(0, 0), cB, voffB); PG8_STAGE(PG8_SA(0, 0), cA, voffA); PG8_STAGE(PG8_SB(0, 1), cB + hstepB, voffB); PG8_STAGE(PG8_SA(0, 1), cA + hstepA, voffA);
;     if (wr == 1) PG8_BAR;
;     PG8_WAIT_V(4); PG8_BAR;
;     PG8_STAGE(PG8_SB(1, 0), cB + kstep, voffB); PG8_STAGE(PG8_SA(1, 0), cA + kstep, voffA); PG8_STAGE(PG8_SB(1, 1), cB + hstepB + kstep, voffB);
;     PG8_WAIT_V(6); PG8_BAR;
;     for (;;) {
;         nxt = S.next(ui + 1); const bool has_next = nxt.nkt != 0;
;         const char* nA = has_next ? (const char*)g.A + (size_t)nxt.pm * tstepA + (size_t)nxt.pn * g.a_pn_off + (size_t)nxt.kt0 * kstep : cA; const char* nB = has_next ? (const char*)g.Bt + (size_t)nxt.pn * tstepB + (size_t)nxt.kt0 * kstep : cB;
;         const int ntc = cur.nkt;
;         for (int t = 0; t < ntc; t += 2) {
;             const bool last = (t == ntc - 2);
;             const char* a1 = cA + (size_t)(t + 1) * kstep;
;             const char* a2 = last ? nA : cA + (size_t)(t + 2) * kstep; const char* b2 = last ? nB : cB + (size_t)(t + 2) * kstep;
;             const char* a3 = a2 + kstep; const char* b3 = b2 + kstep;
;     __device__ __forceinline__ void operator()(const f32x4 (&acc)[2][2][4][2], const Unit& u, int wr, int wc, int fr, int fq) const {
;     ...
;         f32x4 bv[2][2];
; #pragma unroll
;         for (int bj = 0; bj < 2; ++bj)
; #pragma unroll
;             for (int n = 0; n < 2; ++n) bv[bj][n] = *(const f32x4*)(bias + col0 + bj * 128 + 4 * n);
.LBB0_858:
	s_cmp_eq_u32 s61, 0
	s_cselect_b64 s[26:27], -1, 0
	s_ashr_i32 s23, s22, 31
	s_lshl_b64 s[24:25], s[22:23], 20
	s_add_u32 s24, s48, s24
	s_addc_u32 s25, s49, s25
	s_ashr_i32 s21, s20, 31
	s_lshl_b64 s[28:29], s[20:21], 20
	s_add_u32 s28, s50, s28
	s_addc_u32 s29, s51, s29
	s_cmp_lt_i32 s62, 1
	s_cbranch_scc1 .LBB0_850
	s_and_b64 s[40:41], s[26:27], exec
	s_cselect_b32 s21, s37, s25
	s_cselect_b32 s23, s36, s24
	s_cselect_b32 s63, s39, s29
	s_cselect_b32 s65, s38, s28
	s_add_i32 s66, s62, -2
	s_add_u32 s36, s36, 0x80080
	s_addc_u32 s37, s37, 0
	s_add_u32 s67, s38, 0x100
	v_mov_b32_e32 v0, 0
	s_addc_u32 s70, s39, 0
	s_mov_b32 s38, 0
	v_mov_b32_e32 v1, v0
	v_mov_b32_e32 v2, v0
	v_mov_b32_e32 v3, v0
	v_mov_b32_e32 v4, v0
	v_mov_b32_e32 v5, v0
	v_mov_b32_e32 v6, v0
	v_mov_b32_e32 v7, v0
	v_mov_b32_e32 v16, v0
	v_mov_b32_e32 v17, v0
	v_mov_b32_e32 v18, v0
	v_mov_b32_e32 v19, v0
	v_mov_b32_e32 v20, v0
	v_mov_b32_e32 v21, v0
	v_mov_b32_e32 v22, v0
	v_mov_b32_e32 v23, v0
	v_mov_b32_e32 v32, v0
	v_mov_b32_e32 v33, v0
	v_mov_b32_e32 v34, v0
	v_mov_b32_e32 v35, v0
	v_mov_b32_e32 v36, v0
	v_mov_b32_e32 v37, v0
	v_mov_b32_e32 v38, v0
	v_mov_b32_e32 v39, v0
	v_mov_b32_e32 v48, v0
	v_mov_b32_e32 v49, v0
	v_mov_b32_e32 v50, v0
	v_mov_b32_e32 v51, v0
	v_mov_b32_e32 v52, v0
	v_mov_b32_e32 v53, v0
	v_mov_b32_e32 v54, v0
	v_mov_b32_e32 v55, v0
	v_mov_b32_e32 v8, v0
	v_mov_b32_e32 v9, v0
	v_mov_b32_e32 v10, v0
	v_mov_b32_e32 v11, v0
	v_mov_b32_e32 v12, v0
	v_mov_b32_e32 v13, v0
	v_mov_b32_e32 v14, v0
	v_mov_b32_e32 v15, v0
	v_mov_b32_e32 v24, v0
	v_mov_b32_e32 v25, v0
	v_mov_b32_e32 v26, v0
	v_mov_b32_e32 v27, v0
	v_mov_b32_e32 v28, v0
	v_mov_b32_e32 v29, v0
	v_mov_b32_e32 v30, v0
	v_mov_b32_e32 v31, v0
	v_mov_b32_e32 v40, v0
	v_mov_b32_e32 v41, v0
	v_mov_b32_e32 v42, v0
	v_mov_b32_e32 v43, v0
	v_mov_b32_e32 v44, v0
	v_mov_b32_e32 v45, v0
	v_mov_b32_e32 v46, v0
	v_mov_b32_e32 v47, v0
	v_mov_b32_e32 v56, v0
	v_mov_b32_e32 v57, v0
	v_mov_b32_e32 v58, v0
	v_mov_b32_e32 v59, v0
	v_mov_b32_e32 v60, v0
	v_mov_b32_e32 v61, v0
	v_mov_b32_e32 v62, v0
	v_mov_b32_e32 v63, v0
	v_mov_b32_e32 v66, v0
	v_mov_b32_e32 v67, v0
	v_mov_b32_e32 v68, v0
	v_mov_b32_e32 v69, v0
	v_mov_b32_e32 v70, v0
	v_mov_b32_e32 v71, v0
	v_mov_b32_e32 v72, v0
	v_mov_b32_e32 v73, v0
	v_mov_b32_e32 v82, v0
	v_mov_b32_e32 v83, v0
	v_mov_b32_e32 v84, v0
	v_mov_b32_e32 v85, v0
	v_mov_b32_e32 v86, v0
	v_mov_b32_e32 v87, v0
	v_mov_b32_e32 v88, v0
	v_mov_b32_e32 v89, v0
	v_mov_b32_e32 v98, v0
	v_mov_b32_e32 v99, v0
	v_mov_b32_e32 v100, v0
	v_mov_b32_e32 v101, v0
	v_mov_b32_e32 v102, v0
	v_mov_b32_e32 v103, v0
	v_mov_b32_e32 v104, v0
	v_mov_b32_e32 v105, v0
	v_mov_b32_e32 v130, v0
	v_mov_b32_e32 v131, v0
	v_mov_b32_e32 v132, v0
	v_mov_b32_e32 v133, v0
	v_mov_b32_e32 v134, v0
	v_mov_b32_e32 v135, v0
	v_mov_b32_e32 v136, v0
	v_mov_b32_e32 v137, v0
	v_mov_b32_e32 v74, v0
	v_mov_b32_e32 v75, v0
	v_mov_b32_e32 v76, v0
	v_mov_b32_e32 v77, v0
	v_mov_b32_e32 v78, v0
	v_mov_b32_e32 v79, v0
	v_mov_b32_e32 v80, v0
	v_mov_b32_e32 v81, v0
	v_mov_b32_e32 v90, v0
	v_mov_b32_e32 v91, v0
	v_mov_b32_e32 v92, v0
	v_mov_b32_e32 v93, v0
	v_mov_b32_e32 v94, v0
	v_mov_b32_e32 v95, v0
	v_mov_b32_e32 v96, v0
	v_mov_b32_e32 v97, v0
	v_mov_b32_e32 v106, v0
	v_mov_b32_e32 v107, v0
	v_mov_b32_e32 v108, v0
	v_mov_b32_e32 v109, v0
	v_mov_b32_e32 v110, v0
	v_mov_b32_e32 v111, v0
	v_mov_b32_e32 v112, v0
	v_mov_b32_e32 v113, v0
	v_mov_b32_e32 v138, v0
	v_mov_b32_e32 v139, v0
	v_mov_b32_e32 v140, v0
	v_mov_b32_e32 v141, v0
	v_mov_b32_e32 v142, v0
	v_mov_b32_e32 v143, v0
	v_mov_b32_e32 v144, v0
	v_mov_b32_e32 v145, v0
	v_lshl_or_b32 v252, s34, 8, v172
	v_ashrrev_i32_e32 v253, 31, v252
	v_lshl_add_u64 v[252:253], v[252:253], 2, s[18:19]
	global_load_dwordx4 v[240:243], v[252:253], off
	global_load_dwordx4 v[244:247], v[252:253], off offset:16
	global_load_dwordx4 v[248:251], v[252:253], off offset:512
	global_load_dwordx4 v[252:255], v[252:253], off offset:528
